# phase6_up_gemm_epilogue_stores_sc1_nt
# speedup vs baseline: 1.0156x; 1.0156x over previous
.LBB0_1013:
	s_cmp_eq_u32 s77, -1
	v_lshl_add_u32 v146, s50, 8, v150
	s_cbranch_scc1 .LBB0_1016
	v_lshl_add_u32 v157, s76, 10, v152
	ds_read_b32 v162, v157
	v_lshl_or_b32 v148, s77, 8, v153
	v_ashrrev_i32_e32 v147, 31, v146
	v_ashrrev_i32_e32 v149, 31, v148
	v_lshlrev_b64 v[158:159], 13, v[146:147]
	v_lshl_add_u64 v[158:159], s[8:9], 0, v[158:159]
	v_lshlrev_b64 v[164:165], 1, v[148:149]
	s_waitcnt lgkmcnt(0)
	v_pk_mul_f32 v[172:173], v[64:65], v[162:163] op_sel_hi:[1,0]
	v_lshl_add_u64 v[148:149], v[158:159], 0, v[164:165]
	v_pk_mul_f32 v[158:159], v[70:71], v[162:163] op_sel_hi:[1,0]
	v_pk_mul_f32 v[160:161], v[68:69], v[162:163] op_sel_hi:[1,0]
	v_pk_mul_f32 v[166:167], v[66:67], v[162:163] op_sel_hi:[1,0]
	v_max_f32_e32 v163, 0, v173
	v_mul_f32_e32 v163, v163, v163
	v_max_f32_e32 v147, 0, v160
	v_max_f32_e32 v161, 0, v161
	v_max_f32_e32 v158, 0, v158
	v_pk_mul_f32 v[122:123], v[122:123], v[162:163] op_sel_hi:[1,0]
	v_pk_mul_f32 v[120:121], v[120:121], v[162:163] op_sel_hi:[1,0]
	v_max_f32_e32 v160, 0, v172
	v_mul_f32_e32 v147, v147, v147
	v_mul_f32_e32 v161, v161, v161
	v_max_f32_e32 v166, 0, v166
	v_mul_f32_e32 v171, v158, v158
	v_max_f32_e32 v158, 0, v159
	v_max_f32_e32 v159, 0, v167
	v_pk_mul_f32 v[126:127], v[126:127], v[162:163] op_sel_hi:[1,0]
	v_pk_mul_f32 v[124:125], v[124:125], v[162:163] op_sel_hi:[1,0]
	v_max_f32_e32 v120, 0, v120
	v_max_f32_e32 v121, 0, v121
	v_max_f32_e32 v122, 0, v122
	v_mul_f32_e32 v160, v160, v160
	v_mul_f32_e32 v166, v166, v166
	v_mul_f32_e32 v167, v158, v158
	v_mul_f32_e32 v172, v159, v159
	v_cvt_pk_bf16_f32 v158, v147, v161
	v_max_f32_e32 v124, 0, v124
	v_mul_f32_e32 v147, v120, v120
	v_max_f32_e32 v120, 0, v125
	v_mul_f32_e32 v125, v121, v121
	v_max_f32_e32 v121, 0, v126
	v_mul_f32_e32 v126, v122, v122
	v_max_f32_e32 v122, 0, v127
	v_max_f32_e32 v123, 0, v123
	v_cvt_pk_bf16_f32 v159, v171, v167
	v_cvt_pk_bf16_f32 v160, v160, v163
	v_cvt_pk_bf16_f32 v161, v166, v172
	global_store_dwordx4 v[148:149], v[158:161], off sc1 nt
	s_nop 1
	v_mul_f32_e32 v124, v124, v124
	v_mul_f32_e32 v120, v120, v120
	v_mul_f32_e32 v121, v121, v121
	v_mul_f32_e32 v122, v122, v122
	v_mul_f32_e32 v123, v123, v123
	v_cvt_pk_bf16_f32 v120, v124, v120
	v_cvt_pk_bf16_f32 v121, v121, v122
	v_cvt_pk_bf16_f32 v122, v147, v125
	v_cvt_pk_bf16_f32 v123, v126, v123
	v_lshl_add_u64 v[124:125], v[148:149], 0, s[18:19]
	global_store_dwordx4 v[124:125], v[120:123], off sc1 nt
	s_nop 1
	ds_read_b32 v124, v157 offset:64
	v_or_b32_e32 v120, 16, v146
	v_ashrrev_i32_e32 v121, 31, v120
	v_lshlrev_b64 v[120:121], 13, v[120:121]
	v_lshl_add_u64 v[120:121], s[8:9], 0, v[120:121]
	s_waitcnt lgkmcnt(0)
	v_pk_mul_f32 v[160:161], v[56:57], v[124:125] op_sel_hi:[1,0]
	v_lshl_add_u64 v[126:127], v[120:121], 0, v[164:165]
	v_pk_mul_f32 v[120:121], v[62:63], v[124:125] op_sel_hi:[1,0]
	v_pk_mul_f32 v[122:123], v[60:61], v[124:125] op_sel_hi:[1,0]
	v_pk_mul_f32 v[158:159], v[58:59], v[124:125] op_sel_hi:[1,0]
	v_max_f32_e32 v125, 0, v160
	v_max_f32_e32 v122, 0, v122
	v_mul_f32_e32 v125, v125, v125
	v_max_f32_e32 v123, 0, v123
	v_max_f32_e32 v120, 0, v120
	v_mul_f32_e32 v122, v122, v122
	v_max_f32_e32 v147, 0, v161
	v_mul_f32_e32 v123, v123, v123
	v_max_f32_e32 v158, 0, v158
	v_mul_f32_e32 v160, v120, v120
	v_max_f32_e32 v120, 0, v121
	v_max_f32_e32 v121, 0, v159
	v_pk_mul_f32 v[114:115], v[114:115], v[124:125] op_sel_hi:[1,0]
	v_pk_mul_f32 v[112:113], v[112:113], v[124:125] op_sel_hi:[1,0]
	v_mul_f32_e32 v147, v147, v147
	v_mul_f32_e32 v158, v158, v158
	v_mul_f32_e32 v159, v120, v120
	v_mul_f32_e32 v161, v121, v121
	v_cvt_pk_bf16_f32 v120, v122, v123
	v_pk_mul_f32 v[118:119], v[118:119], v[124:125] op_sel_hi:[1,0]
	v_pk_mul_f32 v[116:117], v[116:117], v[124:125] op_sel_hi:[1,0]
	v_max_f32_e32 v112, 0, v112
	v_max_f32_e32 v113, 0, v113
	v_max_f32_e32 v114, 0, v114
	v_cvt_pk_bf16_f32 v121, v160, v159
	v_cvt_pk_bf16_f32 v122, v125, v147
	v_cvt_pk_bf16_f32 v123, v158, v161
	global_store_dwordx4 v[126:127], v[120:123], off sc1 nt
	s_nop 1
	v_max_f32_e32 v116, 0, v116
	v_mul_f32_e32 v120, v112, v112
	v_max_f32_e32 v112, 0, v117
	v_mul_f32_e32 v117, v113, v113
	v_max_f32_e32 v113, 0, v118
	v_mul_f32_e32 v118, v114, v114
	v_max_f32_e32 v114, 0, v119
	v_max_f32_e32 v115, 0, v115
	v_mul_f32_e32 v116, v116, v116
	v_mul_f32_e32 v112, v112, v112
	v_mul_f32_e32 v113, v113, v113
	v_mul_f32_e32 v114, v114, v114
	v_mul_f32_e32 v115, v115, v115
	v_cvt_pk_bf16_f32 v112, v116, v112
	v_cvt_pk_bf16_f32 v113, v113, v114
	v_cvt_pk_bf16_f32 v114, v120, v117
	v_cvt_pk_bf16_f32 v115, v118, v115
	v_lshl_add_u64 v[116:117], v[126:127], 0, s[18:19]
	global_store_dwordx4 v[116:117], v[112:115], off sc1 nt
	s_nop 1
	ds_read_b32 v116, v157 offset:128
	v_or_b32_e32 v112, 32, v146
	v_ashrrev_i32_e32 v113, 31, v112
	v_lshlrev_b64 v[112:113], 13, v[112:113]
	v_lshl_add_u64 v[112:113], s[8:9], 0, v[112:113]
	s_waitcnt lgkmcnt(0)
	v_pk_mul_f32 v[122:123], v[40:41], v[116:117] op_sel_hi:[1,0]
	v_lshl_add_u64 v[118:119], v[112:113], 0, v[164:165]
	v_pk_mul_f32 v[112:113], v[50:51], v[116:117] op_sel_hi:[1,0]
	v_pk_mul_f32 v[114:115], v[48:49], v[116:117] op_sel_hi:[1,0]
	v_pk_mul_f32 v[120:121], v[42:43], v[116:117] op_sel_hi:[1,0]
	v_max_f32_e32 v117, 0, v122
	v_max_f32_e32 v114, 0, v114
	v_mul_f32_e32 v117, v117, v117
	v_max_f32_e32 v115, 0, v115
	v_max_f32_e32 v112, 0, v112
	v_mul_f32_e32 v114, v114, v114
	v_max_f32_e32 v122, 0, v123
	v_mul_f32_e32 v115, v115, v115
	v_max_f32_e32 v120, 0, v120
	v_mul_f32_e32 v123, v112, v112
	v_max_f32_e32 v112, 0, v113
	v_max_f32_e32 v113, 0, v121
	v_pk_mul_f32 v[106:107], v[106:107], v[116:117] op_sel_hi:[1,0]
	v_pk_mul_f32 v[104:105], v[104:105], v[116:117] op_sel_hi:[1,0]
	v_mul_f32_e32 v122, v122, v122
	v_mul_f32_e32 v120, v120, v120
	v_mul_f32_e32 v121, v112, v112
	v_mul_f32_e32 v124, v113, v113
	v_cvt_pk_bf16_f32 v112, v114, v115
	v_pk_mul_f32 v[110:111], v[110:111], v[116:117] op_sel_hi:[1,0]
	v_pk_mul_f32 v[108:109], v[108:109], v[116:117] op_sel_hi:[1,0]
	v_max_f32_e32 v104, 0, v104
	v_max_f32_e32 v105, 0, v105
	v_max_f32_e32 v106, 0, v106
	v_cvt_pk_bf16_f32 v113, v123, v121
	v_cvt_pk_bf16_f32 v114, v117, v122
	v_cvt_pk_bf16_f32 v115, v120, v124
	global_store_dwordx4 v[118:119], v[112:115], off sc1 nt
	s_nop 1
	v_max_f32_e32 v108, 0, v108
	v_mul_f32_e32 v112, v104, v104
	v_max_f32_e32 v104, 0, v109
	v_mul_f32_e32 v109, v105, v105
	v_max_f32_e32 v105, 0, v110
	v_mul_f32_e32 v110, v106, v106
	v_max_f32_e32 v106, 0, v111
	v_max_f32_e32 v107, 0, v107
	v_mul_f32_e32 v108, v108, v108
	v_mul_f32_e32 v104, v104, v104
	v_mul_f32_e32 v105, v105, v105
	v_mul_f32_e32 v106, v106, v106
	v_mul_f32_e32 v107, v107, v107
	v_cvt_pk_bf16_f32 v104, v108, v104
	v_cvt_pk_bf16_f32 v105, v105, v106
	v_cvt_pk_bf16_f32 v106, v112, v109
	v_cvt_pk_bf16_f32 v107, v110, v107
	v_lshl_add_u64 v[108:109], v[118:119], 0, s[18:19]
	global_store_dwordx4 v[108:109], v[104:107], off sc1 nt
	s_nop 1
	ds_read_b32 v108, v157 offset:192
	v_or_b32_e32 v104, 48, v146
	v_ashrrev_i32_e32 v105, 31, v104
	v_lshlrev_b64 v[104:105], 13, v[104:105]
	v_lshl_add_u64 v[104:105], s[8:9], 0, v[104:105]
	s_waitcnt lgkmcnt(0)
	v_pk_mul_f32 v[114:115], v[32:33], v[108:109] op_sel_hi:[1,0]
	v_lshl_add_u64 v[110:111], v[104:105], 0, v[164:165]
	v_pk_mul_f32 v[104:105], v[38:39], v[108:109] op_sel_hi:[1,0]
	v_pk_mul_f32 v[106:107], v[36:37], v[108:109] op_sel_hi:[1,0]
	v_pk_mul_f32 v[112:113], v[34:35], v[108:109] op_sel_hi:[1,0]
	v_max_f32_e32 v109, 0, v114
	v_max_f32_e32 v106, 0, v106
	v_mul_f32_e32 v109, v109, v109
	v_max_f32_e32 v107, 0, v107
	v_max_f32_e32 v104, 0, v104
	v_mul_f32_e32 v106, v106, v106
	v_max_f32_e32 v114, 0, v115
	v_mul_f32_e32 v107, v107, v107
	v_max_f32_e32 v112, 0, v112
	v_mul_f32_e32 v115, v104, v104
	v_max_f32_e32 v104, 0, v105
	v_max_f32_e32 v105, 0, v113
	v_pk_mul_f32 v[98:99], v[98:99], v[108:109] op_sel_hi:[1,0]
	v_pk_mul_f32 v[96:97], v[96:97], v[108:109] op_sel_hi:[1,0]
	v_mul_f32_e32 v114, v114, v114
	v_mul_f32_e32 v112, v112, v112
	v_mul_f32_e32 v113, v104, v104
	v_mul_f32_e32 v116, v105, v105
	v_cvt_pk_bf16_f32 v104, v106, v107
	v_pk_mul_f32 v[102:103], v[102:103], v[108:109] op_sel_hi:[1,0]
	v_pk_mul_f32 v[100:101], v[100:101], v[108:109] op_sel_hi:[1,0]
	v_max_f32_e32 v96, 0, v96
	v_max_f32_e32 v97, 0, v97
	v_max_f32_e32 v98, 0, v98
	v_cvt_pk_bf16_f32 v105, v115, v113
	v_cvt_pk_bf16_f32 v106, v109, v114
	v_cvt_pk_bf16_f32 v107, v112, v116
	global_store_dwordx4 v[110:111], v[104:107], off sc1 nt
	s_nop 1
	v_max_f32_e32 v100, 0, v100
	v_mul_f32_e32 v104, v96, v96
	v_max_f32_e32 v96, 0, v101
	v_mul_f32_e32 v101, v97, v97
	v_max_f32_e32 v97, 0, v102
	v_mul_f32_e32 v102, v98, v98
	v_max_f32_e32 v98, 0, v103
	v_max_f32_e32 v99, 0, v99
	v_mul_f32_e32 v100, v100, v100
	v_mul_f32_e32 v96, v96, v96
	v_mul_f32_e32 v97, v97, v97
	v_mul_f32_e32 v98, v98, v98
	v_mul_f32_e32 v99, v99, v99
	v_cvt_pk_bf16_f32 v96, v100, v96
	v_cvt_pk_bf16_f32 v97, v97, v98
	v_cvt_pk_bf16_f32 v98, v104, v101
	v_cvt_pk_bf16_f32 v99, v102, v99
	v_lshl_add_u64 v[100:101], v[110:111], 0, s[18:19]
	global_store_dwordx4 v[100:101], v[96:99], off sc1 nt
	s_nop 1
	ds_read_b32 v100, v157 offset:512
	v_lshl_add_u64 v[102:103], v[148:149], 0, s[22:23]
	s_waitcnt lgkmcnt(0)
	v_pk_mul_f32 v[106:107], v[24:25], v[100:101] op_sel_hi:[1,0]
	v_pk_mul_f32 v[96:97], v[30:31], v[100:101] op_sel_hi:[1,0]
	v_pk_mul_f32 v[98:99], v[28:29], v[100:101] op_sel_hi:[1,0]
	v_pk_mul_f32 v[104:105], v[26:27], v[100:101] op_sel_hi:[1,0]
	v_max_f32_e32 v101, 0, v106
	v_max_f32_e32 v98, 0, v98
	v_mul_f32_e32 v101, v101, v101
	v_max_f32_e32 v99, 0, v99
	v_max_f32_e32 v96, 0, v96
	v_mul_f32_e32 v98, v98, v98
	v_max_f32_e32 v106, 0, v107
	v_mul_f32_e32 v99, v99, v99
	v_max_f32_e32 v104, 0, v104
	v_mul_f32_e32 v107, v96, v96
	v_max_f32_e32 v96, 0, v97
	v_max_f32_e32 v97, 0, v105
	v_pk_mul_f32 v[90:91], v[90:91], v[100:101] op_sel_hi:[1,0]
	v_pk_mul_f32 v[88:89], v[88:89], v[100:101] op_sel_hi:[1,0]
	v_mul_f32_e32 v106, v106, v106
	v_mul_f32_e32 v104, v104, v104
	v_mul_f32_e32 v105, v96, v96
	v_mul_f32_e32 v108, v97, v97
	v_cvt_pk_bf16_f32 v96, v98, v99
	v_pk_mul_f32 v[94:95], v[94:95], v[100:101] op_sel_hi:[1,0]
	v_pk_mul_f32 v[92:93], v[92:93], v[100:101] op_sel_hi:[1,0]
	v_max_f32_e32 v88, 0, v88
	v_max_f32_e32 v89, 0, v89
	v_max_f32_e32 v90, 0, v90
	v_cvt_pk_bf16_f32 v97, v107, v105
	v_cvt_pk_bf16_f32 v98, v101, v106
	v_cvt_pk_bf16_f32 v99, v104, v108
	global_store_dwordx4 v[102:103], v[96:99], off sc1 nt
	s_nop 1
	v_max_f32_e32 v92, 0, v92
	v_mul_f32_e32 v96, v88, v88
	v_max_f32_e32 v88, 0, v93
	v_mul_f32_e32 v93, v89, v89
	v_max_f32_e32 v89, 0, v94
	v_mul_f32_e32 v94, v90, v90
	v_max_f32_e32 v90, 0, v95
	v_max_f32_e32 v91, 0, v91
	v_mul_f32_e32 v92, v92, v92
	v_mul_f32_e32 v88, v88, v88
	v_mul_f32_e32 v89, v89, v89
	v_mul_f32_e32 v90, v90, v90
	v_mul_f32_e32 v91, v91, v91
	v_cvt_pk_bf16_f32 v88, v92, v88
	v_cvt_pk_bf16_f32 v89, v89, v90
	v_cvt_pk_bf16_f32 v90, v96, v93
	v_cvt_pk_bf16_f32 v91, v94, v91
	v_lshl_add_u64 v[92:93], v[148:149], 0, s[24:25]
	global_store_dwordx4 v[92:93], v[88:91], off sc1 nt
	s_nop 1
	ds_read_b32 v92, v157 offset:576
	v_lshl_add_u64 v[94:95], v[148:149], 0, s[26:27]
	s_waitcnt lgkmcnt(0)
	v_pk_mul_f32 v[98:99], v[16:17], v[92:93] op_sel_hi:[1,0]
	v_pk_mul_f32 v[88:89], v[22:23], v[92:93] op_sel_hi:[1,0]
	v_pk_mul_f32 v[90:91], v[20:21], v[92:93] op_sel_hi:[1,0]
	v_pk_mul_f32 v[96:97], v[18:19], v[92:93] op_sel_hi:[1,0]
	v_max_f32_e32 v93, 0, v98
	v_max_f32_e32 v90, 0, v90
	v_mul_f32_e32 v93, v93, v93
	v_max_f32_e32 v91, 0, v91
	v_max_f32_e32 v88, 0, v88
	v_mul_f32_e32 v90, v90, v90
	v_max_f32_e32 v98, 0, v99
	v_mul_f32_e32 v91, v91, v91
	v_max_f32_e32 v96, 0, v96
	v_mul_f32_e32 v99, v88, v88
	v_max_f32_e32 v88, 0, v89
	v_max_f32_e32 v89, 0, v97
	v_pk_mul_f32 v[82:83], v[82:83], v[92:93] op_sel_hi:[1,0]
	v_pk_mul_f32 v[80:81], v[80:81], v[92:93] op_sel_hi:[1,0]
	v_mul_f32_e32 v98, v98, v98
	v_mul_f32_e32 v96, v96, v96
	v_mul_f32_e32 v97, v88, v88
	v_mul_f32_e32 v100, v89, v89
	v_cvt_pk_bf16_f32 v88, v90, v91
	v_pk_mul_f32 v[86:87], v[86:87], v[92:93] op_sel_hi:[1,0]
	v_pk_mul_f32 v[84:85], v[84:85], v[92:93] op_sel_hi:[1,0]
	v_max_f32_e32 v80, 0, v80
	v_max_f32_e32 v81, 0, v81
	v_max_f32_e32 v82, 0, v82
	v_cvt_pk_bf16_f32 v89, v99, v97
	v_cvt_pk_bf16_f32 v90, v93, v98
	v_cvt_pk_bf16_f32 v91, v96, v100
	global_store_dwordx4 v[94:95], v[88:91], off sc1 nt
	s_nop 1
	v_max_f32_e32 v84, 0, v84
	v_mul_f32_e32 v88, v80, v80
	v_max_f32_e32 v80, 0, v85
	v_mul_f32_e32 v85, v81, v81
	v_max_f32_e32 v81, 0, v86
	v_mul_f32_e32 v86, v82, v82
	v_max_f32_e32 v82, 0, v87
	v_max_f32_e32 v83, 0, v83
	v_mul_f32_e32 v84, v84, v84
	v_mul_f32_e32 v80, v80, v80
	v_mul_f32_e32 v81, v81, v81
	v_mul_f32_e32 v82, v82, v82
	v_mul_f32_e32 v83, v83, v83
	v_cvt_pk_bf16_f32 v80, v84, v80
	v_cvt_pk_bf16_f32 v81, v81, v82
	v_cvt_pk_bf16_f32 v82, v88, v85
	v_cvt_pk_bf16_f32 v83, v86, v83
	v_lshl_add_u64 v[84:85], v[148:149], 0, s[28:29]
	global_store_dwordx4 v[84:85], v[80:83], off sc1 nt
	s_nop 1
	ds_read_b32 v84, v157 offset:640
	v_lshl_add_u64 v[86:87], v[148:149], 0, s[30:31]
	s_waitcnt lgkmcnt(0)
	v_pk_mul_f32 v[90:91], v[8:9], v[84:85] op_sel_hi:[1,0]
	v_pk_mul_f32 v[80:81], v[14:15], v[84:85] op_sel_hi:[1,0]
	v_pk_mul_f32 v[82:83], v[12:13], v[84:85] op_sel_hi:[1,0]
	v_pk_mul_f32 v[88:89], v[10:11], v[84:85] op_sel_hi:[1,0]
	v_max_f32_e32 v85, 0, v90
	v_max_f32_e32 v82, 0, v82
	v_mul_f32_e32 v85, v85, v85
	v_max_f32_e32 v83, 0, v83
	v_max_f32_e32 v80, 0, v80
	v_mul_f32_e32 v82, v82, v82
	v_max_f32_e32 v90, 0, v91
	v_mul_f32_e32 v83, v83, v83
	v_max_f32_e32 v88, 0, v88
	v_mul_f32_e32 v91, v80, v80
	v_max_f32_e32 v80, 0, v81
	v_max_f32_e32 v81, 0, v89
	v_pk_mul_f32 v[74:75], v[74:75], v[84:85] op_sel_hi:[1,0]
	v_pk_mul_f32 v[72:73], v[72:73], v[84:85] op_sel_hi:[1,0]
	v_mul_f32_e32 v90, v90, v90
	v_mul_f32_e32 v88, v88, v88
	v_mul_f32_e32 v89, v80, v80
	v_mul_f32_e32 v92, v81, v81
	v_cvt_pk_bf16_f32 v80, v82, v83
	v_pk_mul_f32 v[78:79], v[78:79], v[84:85] op_sel_hi:[1,0]
	v_pk_mul_f32 v[76:77], v[76:77], v[84:85] op_sel_hi:[1,0]
	v_max_f32_e32 v72, 0, v72
	v_max_f32_e32 v73, 0, v73
	v_max_f32_e32 v74, 0, v74
	v_cvt_pk_bf16_f32 v81, v91, v89
	v_cvt_pk_bf16_f32 v82, v85, v90
	v_cvt_pk_bf16_f32 v83, v88, v92
	global_store_dwordx4 v[86:87], v[80:83], off sc1 nt
	s_nop 1
	v_max_f32_e32 v76, 0, v76
	v_mul_f32_e32 v80, v72, v72
	v_max_f32_e32 v72, 0, v77
	v_mul_f32_e32 v77, v73, v73
	v_max_f32_e32 v73, 0, v78
	v_mul_f32_e32 v78, v74, v74
	v_max_f32_e32 v74, 0, v79
	v_max_f32_e32 v75, 0, v75
	v_mul_f32_e32 v76, v76, v76
	v_mul_f32_e32 v72, v72, v72
	v_mul_f32_e32 v73, v73, v73
	v_mul_f32_e32 v74, v74, v74
	v_mul_f32_e32 v75, v75, v75
	v_cvt_pk_bf16_f32 v72, v76, v72
	v_cvt_pk_bf16_f32 v73, v73, v74
	v_cvt_pk_bf16_f32 v74, v80, v77
	v_cvt_pk_bf16_f32 v75, v78, v75
	v_lshl_add_u64 v[76:77], v[148:149], 0, s[34:35]
	global_store_dwordx4 v[76:77], v[72:75], off sc1 nt
	s_nop 1
	ds_read_b32 v76, v157 offset:704
	v_lshl_add_u64 v[78:79], v[148:149], 0, s[36:37]
	s_waitcnt lgkmcnt(0)
	v_pk_mul_f32 v[82:83], v[0:1], v[76:77] op_sel_hi:[1,0]
	v_pk_mul_f32 v[72:73], v[6:7], v[76:77] op_sel_hi:[1,0]
	v_pk_mul_f32 v[74:75], v[4:5], v[76:77] op_sel_hi:[1,0]
	v_pk_mul_f32 v[80:81], v[2:3], v[76:77] op_sel_hi:[1,0]
	v_max_f32_e32 v77, 0, v82
	v_max_f32_e32 v74, 0, v74
	v_mul_f32_e32 v77, v77, v77
	v_max_f32_e32 v75, 0, v75
	v_max_f32_e32 v72, 0, v72
	v_mul_f32_e32 v74, v74, v74
	v_max_f32_e32 v82, 0, v83
	v_mul_f32_e32 v75, v75, v75
	v_max_f32_e32 v80, 0, v80
	v_mul_f32_e32 v83, v72, v72
	v_max_f32_e32 v72, 0, v73
	v_max_f32_e32 v73, 0, v81
	v_pk_mul_f32 v[46:47], v[46:47], v[76:77] op_sel_hi:[1,0]
	v_pk_mul_f32 v[44:45], v[44:45], v[76:77] op_sel_hi:[1,0]
	v_mul_f32_e32 v82, v82, v82
	v_mul_f32_e32 v80, v80, v80
	v_mul_f32_e32 v81, v72, v72
	v_mul_f32_e32 v84, v73, v73
	v_cvt_pk_bf16_f32 v72, v74, v75
	v_pk_mul_f32 v[54:55], v[54:55], v[76:77] op_sel_hi:[1,0]
	v_pk_mul_f32 v[52:53], v[52:53], v[76:77] op_sel_hi:[1,0]
	v_max_f32_e32 v44, 0, v44
	v_max_f32_e32 v45, 0, v45
	v_max_f32_e32 v46, 0, v46
	v_cvt_pk_bf16_f32 v73, v83, v81
	v_cvt_pk_bf16_f32 v74, v77, v82
	v_cvt_pk_bf16_f32 v75, v80, v84
	global_store_dwordx4 v[78:79], v[72:75], off sc1 nt
	s_nop 1
	v_max_f32_e32 v52, 0, v52
	v_mul_f32_e32 v72, v44, v44
	v_max_f32_e32 v44, 0, v53
	v_mul_f32_e32 v53, v45, v45
	v_max_f32_e32 v45, 0, v54
	v_mul_f32_e32 v54, v46, v46
	v_max_f32_e32 v46, 0, v55
	v_max_f32_e32 v47, 0, v47
	v_mul_f32_e32 v52, v52, v52
	v_mul_f32_e32 v44, v44, v44
	v_mul_f32_e32 v45, v45, v45
	v_mul_f32_e32 v46, v46, v46
	v_mul_f32_e32 v47, v47, v47
	v_cvt_pk_bf16_f32 v44, v52, v44
	v_cvt_pk_bf16_f32 v45, v45, v46
	v_cvt_pk_bf16_f32 v46, v72, v53
	v_cvt_pk_bf16_f32 v47, v54, v47
	v_lshl_add_u64 v[52:53], v[148:149], 0, s[38:39]
	global_store_dwordx4 v[52:53], v[44:47], off sc1 nt
	s_nop 1
	s_cbranch_execz .LBB0_1017
	s_andn2_b64 vcc, exec, s[6:7]
	s_mov_b64 s[0:1], -1
	s_cbranch_vccnz .LBB0_1002
	s_branch .LBB0_1020
